# SWA attention loop: K/V tile addresses also strength-reduced to running pointers
# speedup vs baseline: 1.0105x; 1.0049x over previous
; template <int DQ, int TYPE>
; __device__ __forceinline__ void attn_item(PP p, int layer, int b, int h, int qt, char* lds, const int tid_, unsigned* next_ctr, volatile XLAS unsigned* slot) {
;     ...
;     f32x16 O[4];
; #pragma unroll
;     for (int md = 0; md < 4; ++md)
; #pragma unroll
;         for (int i = 0; i < 16; ++i) O[md][i] = 0.f;
;     float m_run = -1e30f, l_run = 0.f;
;     if (TYPE == 2 && kh == 0) { m_run = p->sinks[layer * 8 + h] * LOG2E; l_run = (hh == 0) ? 1.f : 0.f; }
;     constexpr int GK = (DQ == 192) ? 3 : 4, NG = NKS / GK;
;     A_LSTORE(A, 0); __syncthreads();
;     if (kh == 0) __builtin_amdgcn_s_setprio(2);
; #pragma unroll 1
;     for (int j = j_lo; j <= j_hi; ++j) {
;         const int buf = (j - j_lo) & 1;
;         if (j < j_hi) A_GLOAD(A, j + 1);
;         int mode = 0;
;         if (TYPE == 2) mode = 2;
;         else if (TYPE == 1 && (j >> 2) < own) mode = 3;
;         else if (j >= 2 * qt) mode = 1;
;         const int kbase_pos = 64 * j + 32 * kh;
;         const int qlo = 128 * qt + 32 * qg;
;         bool skip = false;
;         if (mode == 1 || mode == 2) { if (kbase_pos > qlo + 31) skip = true; }
;         if (mode == 2) { if (kbase_pos + 31 <= qlo - 128) skip = true; }
.LBB0_402:
	s_or_b32 s13, s51, 1
	s_ashr_i32 s56, s16, 8
	s_cmp_gt_i32 s12, s13
	v_lshlrev_b32_e32 v155, 2, v3
	s_cbranch_scc1 .LBB0_413
	s_lshl_b32 s13, s56, 5
	v_or_b32_e32 v0, s13, v2
	s_add_i32 s16, s15, 0xf65
	v_mul_lo_u32 v163, v0, s84
	v_add_u32_e32 v0, s16, v2
	s_lshl_b32 s16, s12, 6
	s_add_i32 s59, s16, s13
	v_lshlrev_b32_e32 v16, 3, v3
	v_or_b32_e32 v3, s59, v155
	v_sub_u32_e32 v0, v0, v3
	s_lshl_b32 s14, s14, 7
	v_subrev_u32_e32 v165, s14, v0
	s_add_i32 s14, s14, s59
	s_addk_i32 s14, 0xf080
	v_or_b32_e32 v0, s14, v155
	v_sub_u32_e32 v0, v0, v2
	v_mov_b32_e32 v14, v1
	v_mov_b32_e32 v15, v1
	v_and_b32_e32 v244, 7, v2
	v_lshrrev_b32_e32 v245, 3, v2
	v_mad_u32_u24 v244, v244, 18, v245
	v_mul_u32_u24_e32 v164, 0x88, v244
	v_subrev_u32_e32 v166, s15, v0
	v_mov_b32_e32 v0, v1
	v_mov_b32_e32 v2, v1
	v_mov_b32_e32 v3, v1
	v_mov_b32_e32 v4, v1
	v_mov_b32_e32 v5, v1
	v_mov_b32_e32 v6, v1
	v_mov_b32_e32 v7, v1
	v_mov_b32_e32 v8, v1
	v_mov_b32_e32 v9, v1
	v_mov_b32_e32 v10, v1
	v_mov_b32_e32 v11, v1
	v_mov_b32_e32 v12, v1
	v_mov_b32_e32 v13, v1
	v_lshlrev_b32_e32 v167, 1, v16
	v_mov_b64_e32 v[46:47], v[14:15]
	v_mov_b64_e32 v[30:31], v[14:15]
	v_mov_b64_e32 v[78:79], v[14:15]
	v_mov_b64_e32 v[62:63], v[14:15]
	v_mul_u32_u24_e32 v162, 17, v157
	s_or_b32 s57, s58, 31
	s_addk_i32 s58, 0xff80
	v_mov_b64_e32 v[44:45], v[12:13]
	v_mov_b64_e32 v[42:43], v[10:11]
	v_mov_b64_e32 v[40:41], v[8:9]
	v_mov_b64_e32 v[38:39], v[6:7]
	v_mov_b64_e32 v[36:37], v[4:5]
	v_mov_b64_e32 v[34:35], v[2:3]
	v_mov_b64_e32 v[32:33], v[0:1]
	v_mov_b64_e32 v[28:29], v[12:13]
	v_mov_b64_e32 v[26:27], v[10:11]
	v_mov_b64_e32 v[24:25], v[8:9]
	v_mov_b64_e32 v[22:23], v[6:7]
	v_mov_b64_e32 v[20:21], v[4:5]
	v_mov_b64_e32 v[18:19], v[2:3]
	v_mov_b64_e32 v[16:17], v[0:1]
	v_mov_b64_e32 v[76:77], v[12:13]
	v_mov_b64_e32 v[74:75], v[10:11]
	v_mov_b64_e32 v[72:73], v[8:9]
	v_mov_b64_e32 v[70:71], v[6:7]
	v_mov_b64_e32 v[68:69], v[4:5]
	v_mov_b64_e32 v[66:67], v[2:3]
	v_mov_b64_e32 v[64:65], v[0:1]
	v_mov_b64_e32 v[60:61], v[12:13]
	v_mov_b64_e32 v[58:59], v[10:11]
	v_mov_b64_e32 v[56:57], v[8:9]
	v_mov_b64_e32 v[54:55], v[6:7]
	v_mov_b64_e32 v[52:53], v[4:5]
	v_mov_b64_e32 v[50:51], v[2:3]
	v_mov_b64_e32 v[48:49], v[0:1]
	s_add_i32 s60, s12, 1
	s_ashr_i32 s61, s60, 31
	s_lshl_b64 s[60:61], s[60:61], 6
	s_mov_b32 s98, 0x8000
	s_mov_b32 s99, 0
	v_lshl_add_u64 v[232:233], s[60:61], 0, v[146:147]
	v_lshl_add_u64 v[234:235], s[60:61], 0, v[148:149]
	v_lshl_add_u64 v[236:237], s[60:61], 0, v[150:151]
	v_lshlrev_b64 v[232:233], 9, v[232:233]
	v_lshlrev_b64 v[234:235], 9, v[234:235]
	v_lshlrev_b64 v[236:237], 9, v[236:237]
	v_lshl_add_u64 v[232:233], v[144:145], 0, v[232:233]
	v_lshl_add_u64 v[234:235], v[144:145], 0, v[234:235]
	v_lshl_add_u64 v[236:237], v[152:153], 0, v[236:237]
	s_waitcnt vmcnt(0)
	s_branch .LBB0_406

; template <int DQ, int TYPE>
; __device__ __forceinline__ void attn_item(PP p, int layer, int b, int h, int qt, char* lds, const int tid_, unsigned* next_ctr, volatile XLAS unsigned* slot) {
;     ...
;     for (int j = j_lo; j <= j_hi; ++j) {
;         const int buf = (j - j_lo) & 1;
;         if (j < j_hi) A_GLOAD(A, j + 1);
.LBB0_406:
	s_cmp_gt_i32 s12, s51
	s_cselect_b64 s[14:15], -1, 0
	s_cmp_le_i32 s12, s51
	s_cselect_b64 s[16:17], -1, 0
	s_and_b64 vcc, exec, s[14:15]
	s_cbranch_vccnz .LBB0_408
	global_load_dwordx4 v[96:99], v[232:233], off
	global_load_dwordx4 v[100:103], v[234:235], off
	global_load_dwordx4 v[116:119], v[236:237], off
	global_load_dwordx4 v[128:131], v[236:237], off offset:512
	v_lshl_add_u64 v[232:233], s[98:99], 0, v[232:233]
	v_lshl_add_u64 v[234:235], s[98:99], 0, v[234:235]
	v_lshl_add_u64 v[236:237], s[98:99], 0, v[236:237]
